# P1 in-proj k-loop rewritten: mid-tile barrier, fragments read half a k-tile ahead, LDS-DMA one k-tile ahead, m0 via SALU
# speedup vs baseline: 1.0207x; 1.0207x over previous
.LBB0_142:
	s_mul_hi_i32 s0, s54, 0x2aaaaaab
	s_lshr_b32 s1, s0, 31
	s_ashr_i32 s6, s0, 2
	s_add_i32 s6, s6, s1
	s_mul_i32 s0, s6, 24
	v_readlane_b32 s4, v230, 1
	s_sub_i32 s8, s54, s0
	s_lshl_b32 s0, s6, 20
	v_readlane_b32 s5, v230, 2
	s_add_i32 s1, s4, s0
	v_readlane_b32 s4, v229, 47
	v_mov_b32_e32 v2, v194
	v_readlane_b32 s60, v230, 18
	s_lshl_b32 s2, s8, 20
	s_mul_i32 s4, s4, 0x1800000
	v_readlane_b32 s70, v230, 28
	v_ashrrev_i32_e32 v3, 6, v2
	v_bfe_u32 v4, v2, 3, 3
	v_readlane_b32 s5, v229, 48
	s_add_i32 s4, s2, s4
	v_and_b32_e32 v204, 3, v3
	v_lshlrev_b32_e32 v7, 2, v3
	v_lshlrev_b32_e32 v208, 12, v3
	v_lshlrev_b32_e32 v8, 4, v2
	v_and_b32_e32 v9, 48, v2
	s_movk_i32 s2, 0x70
	v_lshlrev_b32_e32 v3, 17, v3
	v_lshlrev_b32_e32 v11, 12, v4
	s_sub_i32 s1, s1, s70
	v_and_b32_e32 v10, 0x70, v8
	v_bitop3_b32 v8, v8, v9, s2 bitop3:0x6c
	v_or_b32_e32 v12, v11, v3
	v_readfirstlane_b32 s5, v208
	v_add3_u32 v13, v8, s1, v12
	s_mov_b32 m0, s5
	v_add_u32_e32 v12, s4, v12
	buffer_load_dwordx4 v13, s[44:47], 0 offen lds
	v_or_b32_e32 v13, 1, v7
	v_lshl_or_b32 v14, v13, 3, v4
	v_lshrrev_b32_e32 v15, 1, v14
	v_xor_b32_e32 v15, v15, v2
	v_lshlrev_b32_e32 v209, 10, v13
	v_lshlrev_b32_e32 v13, 4, v15
	v_and_b32_e32 v13, 0x70, v13
	v_lshlrev_b32_e32 v14, 12, v14
	v_readfirstlane_b32 s5, v209
	v_add3_u32 v15, v14, s1, v13
	s_mov_b32 m0, s5
	v_bitop3_b32 v9, v12, v10, v9 bitop3:0xf6
	buffer_load_dwordx4 v15, s[44:47], 0 offen lds
	v_or_b32_e32 v15, 2, v7
	v_lshl_or_b32 v16, v15, 3, v4
	v_lshrrev_b32_e32 v17, 1, v16
	v_xor_b32_e32 v17, v17, v2
	v_lshlrev_b32_e32 v210, 10, v15
	v_lshlrev_b32_e32 v15, 4, v17
	v_and_b32_e32 v15, 0x70, v15
	v_lshlrev_b32_e32 v16, 12, v16
	v_readfirstlane_b32 s5, v210
	v_or_b32_e32 v7, 3, v7
	v_add3_u32 v17, v16, s1, v15
	s_mov_b32 m0, s5
	v_lshl_or_b32 v4, v7, 3, v4
	buffer_load_dwordx4 v17, s[44:47], 0 offen lds
	v_lshrrev_b32_e32 v17, 1, v4
	v_xor_b32_e32 v17, v17, v2
	v_lshlrev_b32_e32 v211, 10, v7
	v_lshlrev_b32_e32 v7, 4, v17
	v_and_b32_e32 v7, 0x70, v7
	v_lshlrev_b32_e32 v4, 12, v4
	v_add3_u32 v17, v4, s1, v7
	v_readfirstlane_b32 s1, v211
	s_mov_b32 m0, s1
	v_add_u32_e32 v10, s4, v14
	buffer_load_dwordx4 v17, s[44:47], 0 offen lds
	v_add_u32_e32 v17, 0x8000, v208
	v_or_b32_e32 v10, v13, v10
	v_readfirstlane_b32 s1, v17
	s_mov_b32 m0, s1
	v_add_u32_e32 v4, s4, v4
	buffer_load_dwordx4 v9, s[44:47], 0 offen lds
	v_add_u32_e32 v9, 0x8000, v209
	v_or_b32_e32 v4, v7, v4
	v_readfirstlane_b32 s1, v9
	s_mov_b32 m0, s1
	v_add_u32_e32 v9, 0x8000, v210
	buffer_load_dwordx4 v10, s[44:47], 0 offen lds
	v_add_u32_e32 v10, s4, v16
	v_readfirstlane_b32 s1, v9
	v_add_u32_e32 v9, 0x8000, v211
	v_or_b32_e32 v10, v15, v10
	s_mov_b32 m0, s1
	v_readfirstlane_b32 s1, v9
	buffer_load_dwordx4 v10, s[44:47], 0 offen lds
	s_mov_b32 m0, s1
	s_lshl_b32 s1, s54, 20
	buffer_load_dwordx4 v4, s[44:47], 0 offen lds
	s_add_i32 s4, s57, s1
	v_bfe_u32 v205, v2, 4, 2
	v_and_b32_e32 v1, 15, v2
	v_lshrrev_b32_e32 v5, 1, v2
	v_bfe_u32 v6, v2, 1, 3
	v_ashrrev_i32_e32 v212, 8, v2
	v_add_u32_e32 v2, s4, v3
	v_readlane_b32 s5, v229, 15
	v_add3_u32 v2, v2, v11, v7
	s_mul_i32 s4, s6, 0x1800000
	s_add_i32 s5, s5, s1
	v_subrev_u32_e32 v216, s4, v2
	v_add_u32_e32 v2, s5, v3
	v_readlane_b32 s5, v229, 17
	v_add3_u32 v2, v2, v11, v15
	s_add_i32 s5, s5, s1
	v_subrev_u32_e32 v217, s4, v2
	v_add_u32_e32 v2, s5, v3
	v_readlane_b32 s5, v229, 46
	v_add3_u32 v2, v2, v11, v13
	s_add_i32 s1, s1, s5
	v_subrev_u32_e32 v218, s4, v2
	v_add_u32_e32 v2, s1, v8
	v_readlane_b32 s1, v229, 14
	v_add3_u32 v2, v2, v3, v11
	s_add_i32 s1, s1, s0
	v_subrev_u32_e32 v219, s4, v2
	v_add_u32_e32 v2, s1, v3
	v_readlane_b32 s1, v229, 16
	s_add_i32 s1, s1, s0
	v_add3_u32 v220, v2, v11, v7
	v_add_u32_e32 v2, s1, v3
	v_readlane_b32 s1, v229, 18
	s_add_i32 s1, s1, s0
	v_add3_u32 v221, v2, v11, v15
	v_add_u32_e32 v2, s1, v3
	v_readlane_b32 s1, v229, 19
	s_add_i32 s0, s0, s1
	v_bitop3_b32 v5, v205, v5, 7 bitop3:0x78
	v_bitop3_b32 v6, v205, v6, 4 bitop3:0x36
	v_add3_u32 v222, v2, v11, v13
	v_add_u32_e32 v2, s0, v8
	v_mov_b32_e32 v34, 0
	v_lshlrev_b32_e32 v206, 7, v1
	v_lshlrev_b32_e32 v207, 13, v204
	s_mov_b32 s2, 0
	v_lshlrev_b32_e32 v213, 14, v212
	v_lshlrev_b32_e32 v214, 4, v5
	v_lshlrev_b32_e32 v215, 4, v6
	v_add3_u32 v223, v2, v3, v11
	s_mov_b32 s7, 0
	v_mov_b32_e32 v35, v34
	v_mov_b32_e32 v36, v34
	v_mov_b32_e32 v37, v34
	v_mov_b32_e32 v38, v34
	v_mov_b32_e32 v39, v34
	v_mov_b32_e32 v40, v34
	v_mov_b32_e32 v41, v34
	v_mov_b32_e32 v42, v34
	v_mov_b32_e32 v43, v34
	v_mov_b32_e32 v44, v34
	v_mov_b32_e32 v45, v34
	v_mov_b32_e32 v46, v34
	v_mov_b32_e32 v47, v34
	v_mov_b32_e32 v48, v34
	v_mov_b32_e32 v49, v34
	v_mov_b32_e32 v50, v34
	v_mov_b32_e32 v51, v34
	v_mov_b32_e32 v52, v34
	v_mov_b32_e32 v53, v34
	v_mov_b32_e32 v54, v34
	v_mov_b32_e32 v55, v34
	v_mov_b32_e32 v56, v34
	v_mov_b32_e32 v57, v34
	v_mov_b32_e32 v58, v34
	v_mov_b32_e32 v59, v34
	v_mov_b32_e32 v60, v34
	v_mov_b32_e32 v61, v34
	v_mov_b32_e32 v62, v34
	v_mov_b32_e32 v63, v34
	v_mov_b32_e32 v64, v34
	v_mov_b32_e32 v65, v34
	v_mov_b32_e32 v66, v34
	v_mov_b32_e32 v67, v34
	v_mov_b32_e32 v68, v34
	v_mov_b32_e32 v69, v34
	v_mov_b32_e32 v70, v34
	v_mov_b32_e32 v71, v34
	v_mov_b32_e32 v72, v34
	v_mov_b32_e32 v73, v34
	v_mov_b32_e32 v74, v34
	v_mov_b32_e32 v75, v34
	v_mov_b32_e32 v76, v34
	v_mov_b32_e32 v77, v34
	v_mov_b32_e32 v78, v34
	v_mov_b32_e32 v79, v34
	v_mov_b32_e32 v80, v34
	v_mov_b32_e32 v81, v34
	v_mov_b32_e32 v82, v34
	v_mov_b32_e32 v83, v34
	v_mov_b32_e32 v84, v34
	v_mov_b32_e32 v85, v34
	v_mov_b32_e32 v86, v34
	v_mov_b32_e32 v87, v34
	v_mov_b32_e32 v88, v34
	v_mov_b32_e32 v89, v34
	v_mov_b32_e32 v90, v34
	v_mov_b32_e32 v91, v34
	v_mov_b32_e32 v92, v34
	v_mov_b32_e32 v93, v34
	v_mov_b32_e32 v94, v34
	v_mov_b32_e32 v95, v34
	v_mov_b32_e32 v96, v34
	v_mov_b32_e32 v97, v34
	v_mov_b32_e32 v98, v34
	v_mov_b32_e32 v99, v34
	v_mov_b32_e32 v100, v34
	v_mov_b32_e32 v101, v34
	v_mov_b32_e32 v102, v34
	v_mov_b32_e32 v103, v34
	v_mov_b32_e32 v104, v34
	v_mov_b32_e32 v105, v34
	v_mov_b32_e32 v106, v34
	v_mov_b32_e32 v107, v34
	v_mov_b32_e32 v108, v34
	v_mov_b32_e32 v109, v34
	v_mov_b32_e32 v110, v34
	v_mov_b32_e32 v111, v34
	v_mov_b32_e32 v112, v34
	v_mov_b32_e32 v113, v34
	v_mov_b32_e32 v114, v34
	v_mov_b32_e32 v115, v34
	v_mov_b32_e32 v116, v34
	v_mov_b32_e32 v117, v34
	v_mov_b32_e32 v118, v34
	v_mov_b32_e32 v119, v34
	v_mov_b32_e32 v120, v34
	v_mov_b32_e32 v121, v34
	v_mov_b32_e32 v122, v34
	v_mov_b32_e32 v123, v34
	v_mov_b32_e32 v124, v34
	v_mov_b32_e32 v125, v34
	v_mov_b32_e32 v126, v34
	v_mov_b32_e32 v127, v34
	v_mov_b32_e32 v128, v34
	v_mov_b32_e32 v129, v34
	v_mov_b32_e32 v30, v34
	v_mov_b32_e32 v31, v34
	v_mov_b32_e32 v32, v34
	v_mov_b32_e32 v33, v34
	v_mov_b32_e32 v26, v34
	v_mov_b32_e32 v27, v34
	v_mov_b32_e32 v28, v34
	v_mov_b32_e32 v29, v34
	v_mov_b32_e32 v22, v34
	v_mov_b32_e32 v23, v34
	v_mov_b32_e32 v24, v34
	v_mov_b32_e32 v25, v34
	v_mov_b32_e32 v18, v34
	v_mov_b32_e32 v19, v34
	v_mov_b32_e32 v20, v34
	v_mov_b32_e32 v21, v34
	v_mov_b32_e32 v14, v34
	v_mov_b32_e32 v15, v34
	v_mov_b32_e32 v16, v34
	v_mov_b32_e32 v17, v34
	v_mov_b32_e32 v10, v34
	v_mov_b32_e32 v11, v34
	v_mov_b32_e32 v12, v34
	v_mov_b32_e32 v13, v34
	v_mov_b32_e32 v6, v34
	v_mov_b32_e32 v7, v34
	v_mov_b32_e32 v8, v34
	v_mov_b32_e32 v9, v34
	v_mov_b32_e32 v2, v34
	v_mov_b32_e32 v3, v34
	v_mov_b32_e32 v4, v34
	v_mov_b32_e32 v5, v34
	v_readlane_b32 s61, v230, 19
	v_readlane_b32 s62, v230, 20
	v_readlane_b32 s63, v230, 21
	v_readlane_b32 s64, v230, 22
	v_readlane_b32 s65, v230, 23
	v_readlane_b32 s66, v230, 24
	v_readlane_b32 s67, v230, 25
	v_readlane_b32 s68, v230, 26
	v_readlane_b32 s69, v230, 27
	v_readlane_b32 s71, v230, 29
	v_readlane_b32 s72, v230, 30
	v_readlane_b32 s73, v230, 31
	v_readlane_b32 s74, v230, 32
	v_readlane_b32 s75, v230, 33
	v_readfirstlane_b32 s12, v208
	v_add3_u32 v250, v213, v206, v214
	v_add3_u32 v251, v213, v206, v215
	v_add3_u32 v252, v207, v206, v214
	v_add3_u32 v253, v207, v206, v215
	s_mov_b32 s10, 0
	s_mov_b32 s11, 0
	s_waitcnt vmcnt(0)
	s_barrier
	s_add_i32 s14, s12, 0x10000
	s_mov_b32 m0, s14
	s_nop 0
	buffer_load_dwordx4 v223, s[44:47], s11 offen lds
	s_add_u32 m0, s14, 0x400
	s_nop 0
	buffer_load_dwordx4 v222, s[44:47], s11 offen lds
	s_add_u32 m0, s14, 0x800
	s_nop 0
	buffer_load_dwordx4 v221, s[44:47], s11 offen lds
	s_add_u32 m0, s14, 0xc00
	s_nop 0
	buffer_load_dwordx4 v220, s[44:47], s11 offen lds
	s_add_u32 m0, s14, 0x8000
	s_nop 0
	buffer_load_dwordx4 v219, s[44:47], s11 offen lds
	s_add_u32 m0, s14, 0x8400
	s_nop 0
	buffer_load_dwordx4 v218, s[44:47], s11 offen lds
	s_add_u32 m0, s14, 0x8800
	s_nop 0
	buffer_load_dwordx4 v217, s[44:47], s11 offen lds
	s_add_u32 m0, s14, 0x8c00
	s_nop 0
	buffer_load_dwordx4 v216, s[44:47], s11 offen lds
	s_movk_i32 s11, 0x80
	ds_read_b128 v[162:165], v252 offset:32768
	ds_read_b128 v[166:169], v252 offset:34816
	ds_read_b128 v[170:173], v252 offset:36864
	ds_read_b128 v[174:177], v252 offset:38912
	ds_read_b128 v[146:149], v250 offset:8192
	ds_read_b128 v[150:153], v250 offset:10240
	ds_read_b128 v[154:157], v250 offset:12288
	ds_read_b128 v[158:161], v250 offset:14336
	ds_read_b128 v[130:133], v250
	ds_read_b128 v[134:137], v250 offset:2048
	ds_read_b128 v[138:141], v250 offset:4096
	ds_read_b128 v[142:145], v250 offset:6144
	s_movk_i32 s15, 30
.Lp1_steady:
	s_waitcnt lgkmcnt(4)
	v_add_u32_e32 v248, s10, v251
	v_add_u32_e32 v249, s10, v253
	ds_read_b128 v[178:181], v249 offset:32768
	ds_read_b128 v[182:185], v249 offset:34816
	ds_read_b128 v[186:189], v249 offset:36864
	ds_read_b128 v[190:193], v249 offset:38912
	ds_read_b128 v[232:235], v248
	ds_read_b128 v[236:239], v248 offset:2048
	ds_read_b128 v[240:243], v248 offset:4096
	ds_read_b128 v[244:247], v248 offset:6144
	s_waitcnt lgkmcnt(8)
	v_mfma_f32_16x16x32_bf16 v[126:129], v[162:165], v[130:133], v[126:129]
	v_mfma_f32_16x16x32_bf16 v[122:125], v[166:169], v[130:133], v[122:125]
	v_mfma_f32_16x16x32_bf16 v[118:121], v[170:173], v[130:133], v[118:121]
	v_mfma_f32_16x16x32_bf16 v[114:117], v[174:177], v[130:133], v[114:117]
	v_mfma_f32_16x16x32_bf16 v[110:113], v[162:165], v[134:137], v[110:113]
	v_mfma_f32_16x16x32_bf16 v[106:109], v[166:169], v[134:137], v[106:109]
	v_mfma_f32_16x16x32_bf16 v[102:105], v[170:173], v[134:137], v[102:105]
	v_mfma_f32_16x16x32_bf16 v[98:101], v[174:177], v[134:137], v[98:101]
	v_mfma_f32_16x16x32_bf16 v[94:97], v[162:165], v[138:141], v[94:97]
	v_mfma_f32_16x16x32_bf16 v[90:93], v[166:169], v[138:141], v[90:93]
	v_mfma_f32_16x16x32_bf16 v[86:89], v[170:173], v[138:141], v[86:89]
	v_mfma_f32_16x16x32_bf16 v[82:85], v[174:177], v[138:141], v[82:85]
	v_mfma_f32_16x16x32_bf16 v[78:81], v[162:165], v[142:145], v[78:81]
	v_mfma_f32_16x16x32_bf16 v[74:77], v[166:169], v[142:145], v[74:77]
	v_mfma_f32_16x16x32_bf16 v[70:73], v[170:173], v[142:145], v[70:73]
	v_mfma_f32_16x16x32_bf16 v[66:69], v[174:177], v[142:145], v[66:69]
	ds_read_b128 v[130:133], v248 offset:8192
	ds_read_b128 v[134:137], v248 offset:10240
	ds_read_b128 v[138:141], v248 offset:12288
	ds_read_b128 v[142:145], v248 offset:14336
	v_mfma_f32_16x16x32_bf16 v[62:65], v[162:165], v[146:149], v[62:65]
	v_mfma_f32_16x16x32_bf16 v[58:61], v[166:169], v[146:149], v[58:61]
	v_mfma_f32_16x16x32_bf16 v[54:57], v[170:173], v[146:149], v[54:57]
	v_mfma_f32_16x16x32_bf16 v[50:53], v[174:177], v[146:149], v[50:53]
	v_mfma_f32_16x16x32_bf16 v[46:49], v[162:165], v[150:153], v[46:49]
	v_mfma_f32_16x16x32_bf16 v[42:45], v[166:169], v[150:153], v[42:45]
	v_mfma_f32_16x16x32_bf16 v[38:41], v[170:173], v[150:153], v[38:41]
	v_mfma_f32_16x16x32_bf16 v[34:37], v[174:177], v[150:153], v[34:37]
	v_mfma_f32_16x16x32_bf16 v[30:33], v[162:165], v[154:157], v[30:33]
	v_mfma_f32_16x16x32_bf16 v[26:29], v[166:169], v[154:157], v[26:29]
	v_mfma_f32_16x16x32_bf16 v[22:25], v[170:173], v[154:157], v[22:25]
	v_mfma_f32_16x16x32_bf16 v[18:21], v[174:177], v[154:157], v[18:21]
	v_mfma_f32_16x16x32_bf16 v[14:17], v[162:165], v[158:161], v[14:17]
	v_mfma_f32_16x16x32_bf16 v[10:13], v[166:169], v[158:161], v[10:13]
	v_mfma_f32_16x16x32_bf16 v[6:9], v[170:173], v[158:161], v[6:9]
	v_mfma_f32_16x16x32_bf16 v[2:5], v[174:177], v[158:161], v[2:5]
	s_waitcnt lgkmcnt(0)
	s_waitcnt vmcnt(0)
	s_barrier
	s_xor_b32 s13, s10, 0x10000
	s_add_i32 s14, s10, s12
	v_add_u32_e32 v248, s13, v250
	v_add_u32_e32 v249, s13, v252
	ds_read_b128 v[162:165], v249 offset:32768
	ds_read_b128 v[166:169], v249 offset:34816
	ds_read_b128 v[170:173], v249 offset:36864
	ds_read_b128 v[174:177], v249 offset:38912
	ds_read_b128 v[146:149], v248 offset:8192
	ds_read_b128 v[150:153], v248 offset:10240
	ds_read_b128 v[154:157], v248 offset:12288
	ds_read_b128 v[158:161], v248 offset:14336
	v_mfma_f32_16x16x32_bf16 v[62:65], v[178:181], v[130:133], v[62:65]
	s_mov_b32 m0, s14
	v_mfma_f32_16x16x32_bf16 v[58:61], v[182:185], v[130:133], v[58:61]
	buffer_load_dwordx4 v223, s[44:47], s11 offen lds
	v_mfma_f32_16x16x32_bf16 v[54:57], v[186:189], v[130:133], v[54:57]
	v_mfma_f32_16x16x32_bf16 v[50:53], v[190:193], v[130:133], v[50:53]
	v_mfma_f32_16x16x32_bf16 v[46:49], v[178:181], v[134:137], v[46:49]
	s_add_u32 m0, s14, 0x400
	v_mfma_f32_16x16x32_bf16 v[42:45], v[182:185], v[134:137], v[42:45]
	buffer_load_dwordx4 v222, s[44:47], s11 offen lds
	v_mfma_f32_16x16x32_bf16 v[38:41], v[186:189], v[134:137], v[38:41]
	v_mfma_f32_16x16x32_bf16 v[34:37], v[190:193], v[134:137], v[34:37]
	v_mfma_f32_16x16x32_bf16 v[30:33], v[178:181], v[138:141], v[30:33]
	s_add_u32 m0, s14, 0x800
	v_mfma_f32_16x16x32_bf16 v[26:29], v[182:185], v[138:141], v[26:29]
	buffer_load_dwordx4 v221, s[44:47], s11 offen lds
	v_mfma_f32_16x16x32_bf16 v[22:25], v[186:189], v[138:141], v[22:25]
	v_mfma_f32_16x16x32_bf16 v[18:21], v[190:193], v[138:141], v[18:21]
	v_mfma_f32_16x16x32_bf16 v[14:17], v[178:181], v[142:145], v[14:17]
	s_add_u32 m0, s14, 0xc00
	v_mfma_f32_16x16x32_bf16 v[10:13], v[182:185], v[142:145], v[10:13]
	buffer_load_dwordx4 v220, s[44:47], s11 offen lds
	v_mfma_f32_16x16x32_bf16 v[6:9], v[186:189], v[142:145], v[6:9]
	v_mfma_f32_16x16x32_bf16 v[2:5], v[190:193], v[142:145], v[2:5]
	ds_read_b128 v[130:133], v248
	ds_read_b128 v[134:137], v248 offset:2048
	ds_read_b128 v[138:141], v248 offset:4096
	ds_read_b128 v[142:145], v248 offset:6144
	v_mfma_f32_16x16x32_bf16 v[126:129], v[178:181], v[232:235], v[126:129]
	s_add_u32 m0, s14, 0x8000
	v_mfma_f32_16x16x32_bf16 v[122:125], v[182:185], v[232:235], v[122:125]
	buffer_load_dwordx4 v219, s[44:47], s11 offen lds
	v_mfma_f32_16x16x32_bf16 v[118:121], v[186:189], v[232:235], v[118:121]
	v_mfma_f32_16x16x32_bf16 v[114:117], v[190:193], v[232:235], v[114:117]
	v_mfma_f32_16x16x32_bf16 v[110:113], v[178:181], v[236:239], v[110:113]
	s_add_u32 m0, s14, 0x8400
	v_mfma_f32_16x16x32_bf16 v[106:109], v[182:185], v[236:239], v[106:109]
	buffer_load_dwordx4 v218, s[44:47], s11 offen lds
	v_mfma_f32_16x16x32_bf16 v[102:105], v[186:189], v[236:239], v[102:105]
	v_mfma_f32_16x16x32_bf16 v[98:101], v[190:193], v[236:239], v[98:101]
	v_mfma_f32_16x16x32_bf16 v[94:97], v[178:181], v[240:243], v[94:97]
	s_add_u32 m0, s14, 0x8800
	v_mfma_f32_16x16x32_bf16 v[90:93], v[182:185], v[240:243], v[90:93]
	buffer_load_dwordx4 v217, s[44:47], s11 offen lds
	v_mfma_f32_16x16x32_bf16 v[86:89], v[186:189], v[240:243], v[86:89]
	v_mfma_f32_16x16x32_bf16 v[82:85], v[190:193], v[240:243], v[82:85]
	v_mfma_f32_16x16x32_bf16 v[78:81], v[178:181], v[244:247], v[78:81]
	s_add_u32 m0, s14, 0x8c00
	v_mfma_f32_16x16x32_bf16 v[74:77], v[182:185], v[244:247], v[74:77]
	buffer_load_dwordx4 v216, s[44:47], s11 offen lds
	v_mfma_f32_16x16x32_bf16 v[70:73], v[186:189], v[244:247], v[70:73]
	v_mfma_f32_16x16x32_bf16 v[66:69], v[190:193], v[244:247], v[66:69]
	s_xor_b32 s10, s10, 0x10000
	s_addk_i32 s11, 0x80
	s_add_i32 s15, s15, -1
	s_cmp_lg_u32 s15, 0
	s_cbranch_scc1 .Lp1_steady
	s_waitcnt lgkmcnt(4)
	v_add_u32_e32 v248, s10, v251
	v_add_u32_e32 v249, s10, v253
	ds_read_b128 v[178:181], v249 offset:32768
	ds_read_b128 v[182:185], v249 offset:34816
	ds_read_b128 v[186:189], v249 offset:36864
	ds_read_b128 v[190:193], v249 offset:38912
	ds_read_b128 v[232:235], v248
	ds_read_b128 v[236:239], v248 offset:2048
	ds_read_b128 v[240:243], v248 offset:4096
	ds_read_b128 v[244:247], v248 offset:6144
	s_waitcnt lgkmcnt(8)
	v_mfma_f32_16x16x32_bf16 v[126:129], v[162:165], v[130:133], v[126:129]
	v_mfma_f32_16x16x32_bf16 v[122:125], v[166:169], v[130:133], v[122:125]
	v_mfma_f32_16x16x32_bf16 v[118:121], v[170:173], v[130:133], v[118:121]
	v_mfma_f32_16x16x32_bf16 v[114:117], v[174:177], v[130:133], v[114:117]
	v_mfma_f32_16x16x32_bf16 v[110:113], v[162:165], v[134:137], v[110:113]
	v_mfma_f32_16x16x32_bf16 v[106:109], v[166:169], v[134:137], v[106:109]
	v_mfma_f32_16x16x32_bf16 v[102:105], v[170:173], v[134:137], v[102:105]
	v_mfma_f32_16x16x32_bf16 v[98:101], v[174:177], v[134:137], v[98:101]
	v_mfma_f32_16x16x32_bf16 v[94:97], v[162:165], v[138:141], v[94:97]
	v_mfma_f32_16x16x32_bf16 v[90:93], v[166:169], v[138:141], v[90:93]
	v_mfma_f32_16x16x32_bf16 v[86:89], v[170:173], v[138:141], v[86:89]
	v_mfma_f32_16x16x32_bf16 v[82:85], v[174:177], v[138:141], v[82:85]
	v_mfma_f32_16x16x32_bf16 v[78:81], v[162:165], v[142:145], v[78:81]
	v_mfma_f32_16x16x32_bf16 v[74:77], v[166:169], v[142:145], v[74:77]
	v_mfma_f32_16x16x32_bf16 v[70:73], v[170:173], v[142:145], v[70:73]
	v_mfma_f32_16x16x32_bf16 v[66:69], v[174:177], v[142:145], v[66:69]
	ds_read_b128 v[130:133], v248 offset:8192
	ds_read_b128 v[134:137], v248 offset:10240
	ds_read_b128 v[138:141], v248 offset:12288
	ds_read_b128 v[142:145], v248 offset:14336
	v_mfma_f32_16x16x32_bf16 v[62:65], v[162:165], v[146:149], v[62:65]
	v_mfma_f32_16x16x32_bf16 v[58:61], v[166:169], v[146:149], v[58:61]
	v_mfma_f32_16x16x32_bf16 v[54:57], v[170:173], v[146:149], v[54:57]
	v_mfma_f32_16x16x32_bf16 v[50:53], v[174:177], v[146:149], v[50:53]
	v_mfma_f32_16x16x32_bf16 v[46:49], v[162:165], v[150:153], v[46:49]
	v_mfma_f32_16x16x32_bf16 v[42:45], v[166:169], v[150:153], v[42:45]
	v_mfma_f32_16x16x32_bf16 v[38:41], v[170:173], v[150:153], v[38:41]
	v_mfma_f32_16x16x32_bf16 v[34:37], v[174:177], v[150:153], v[34:37]
	v_mfma_f32_16x16x32_bf16 v[30:33], v[162:165], v[154:157], v[30:33]
	v_mfma_f32_16x16x32_bf16 v[26:29], v[166:169], v[154:157], v[26:29]
	v_mfma_f32_16x16x32_bf16 v[22:25], v[170:173], v[154:157], v[22:25]
	v_mfma_f32_16x16x32_bf16 v[18:21], v[174:177], v[154:157], v[18:21]
	v_mfma_f32_16x16x32_bf16 v[14:17], v[162:165], v[158:161], v[14:17]
	v_mfma_f32_16x16x32_bf16 v[10:13], v[166:169], v[158:161], v[10:13]
	v_mfma_f32_16x16x32_bf16 v[6:9], v[170:173], v[158:161], v[6:9]
	v_mfma_f32_16x16x32_bf16 v[2:5], v[174:177], v[158:161], v[2:5]
	s_waitcnt lgkmcnt(0)
	s_waitcnt vmcnt(0)
	s_barrier
	s_xor_b32 s13, s10, 0x10000
	v_add_u32_e32 v248, s13, v250
	v_add_u32_e32 v249, s13, v252
	ds_read_b128 v[162:165], v249 offset:32768
	ds_read_b128 v[166:169], v249 offset:34816
	ds_read_b128 v[170:173], v249 offset:36864
	ds_read_b128 v[174:177], v249 offset:38912
	ds_read_b128 v[146:149], v248 offset:8192
	ds_read_b128 v[150:153], v248 offset:10240
	ds_read_b128 v[154:157], v248 offset:12288
	ds_read_b128 v[158:161], v248 offset:14336
	v_mfma_f32_16x16x32_bf16 v[62:65], v[178:181], v[130:133], v[62:65]
	v_mfma_f32_16x16x32_bf16 v[58:61], v[182:185], v[130:133], v[58:61]
	v_mfma_f32_16x16x32_bf16 v[54:57], v[186:189], v[130:133], v[54:57]
	v_mfma_f32_16x16x32_bf16 v[50:53], v[190:193], v[130:133], v[50:53]
	v_mfma_f32_16x16x32_bf16 v[46:49], v[178:181], v[134:137], v[46:49]
	v_mfma_f32_16x16x32_bf16 v[42:45], v[182:185], v[134:137], v[42:45]
	v_mfma_f32_16x16x32_bf16 v[38:41], v[186:189], v[134:137], v[38:41]
	v_mfma_f32_16x16x32_bf16 v[34:37], v[190:193], v[134:137], v[34:37]
	v_mfma_f32_16x16x32_bf16 v[30:33], v[178:181], v[138:141], v[30:33]
	v_mfma_f32_16x16x32_bf16 v[26:29], v[182:185], v[138:141], v[26:29]
	v_mfma_f32_16x16x32_bf16 v[22:25], v[186:189], v[138:141], v[22:25]
	v_mfma_f32_16x16x32_bf16 v[18:21], v[190:193], v[138:141], v[18:21]
	v_mfma_f32_16x16x32_bf16 v[14:17], v[178:181], v[142:145], v[14:17]
	v_mfma_f32_16x16x32_bf16 v[10:13], v[182:185], v[142:145], v[10:13]
	v_mfma_f32_16x16x32_bf16 v[6:9], v[186:189], v[142:145], v[6:9]
	v_mfma_f32_16x16x32_bf16 v[2:5], v[190:193], v[142:145], v[2:5]
	ds_read_b128 v[130:133], v248
	ds_read_b128 v[134:137], v248 offset:2048
	ds_read_b128 v[138:141], v248 offset:4096
	ds_read_b128 v[142:145], v248 offset:6144
	v_mfma_f32_16x16x32_bf16 v[126:129], v[178:181], v[232:235], v[126:129]
	v_mfma_f32_16x16x32_bf16 v[122:125], v[182:185], v[232:235], v[122:125]
	v_mfma_f32_16x16x32_bf16 v[118:121], v[186:189], v[232:235], v[118:121]
	v_mfma_f32_16x16x32_bf16 v[114:117], v[190:193], v[232:235], v[114:117]
	v_mfma_f32_16x16x32_bf16 v[110:113], v[178:181], v[236:239], v[110:113]
	v_mfma_f32_16x16x32_bf16 v[106:109], v[182:185], v[236:239], v[106:109]
	v_mfma_f32_16x16x32_bf16 v[102:105], v[186:189], v[236:239], v[102:105]
	v_mfma_f32_16x16x32_bf16 v[98:101], v[190:193], v[236:239], v[98:101]
	v_mfma_f32_16x16x32_bf16 v[94:97], v[178:181], v[240:243], v[94:97]
	v_mfma_f32_16x16x32_bf16 v[90:93], v[182:185], v[240:243], v[90:93]
	v_mfma_f32_16x16x32_bf16 v[86:89], v[186:189], v[240:243], v[86:89]
	v_mfma_f32_16x16x32_bf16 v[82:85], v[190:193], v[240:243], v[82:85]
	v_mfma_f32_16x16x32_bf16 v[78:81], v[178:181], v[244:247], v[78:81]
	v_mfma_f32_16x16x32_bf16 v[74:77], v[182:185], v[244:247], v[74:77]
	v_mfma_f32_16x16x32_bf16 v[70:73], v[186:189], v[244:247], v[70:73]
	v_mfma_f32_16x16x32_bf16 v[66:69], v[190:193], v[244:247], v[66:69]
	s_xor_b32 s10, s10, 0x10000
	s_waitcnt lgkmcnt(4)
	v_add_u32_e32 v248, s10, v251
	v_add_u32_e32 v249, s10, v253
	ds_read_b128 v[178:181], v249 offset:32768
	ds_read_b128 v[182:185], v249 offset:34816
	ds_read_b128 v[186:189], v249 offset:36864
	ds_read_b128 v[190:193], v249 offset:38912
	ds_read_b128 v[232:235], v248
	ds_read_b128 v[236:239], v248 offset:2048
	ds_read_b128 v[240:243], v248 offset:4096
	ds_read_b128 v[244:247], v248 offset:6144
	s_waitcnt lgkmcnt(8)
	v_mfma_f32_16x16x32_bf16 v[126:129], v[162:165], v[130:133], v[126:129]
	v_mfma_f32_16x16x32_bf16 v[122:125], v[166:169], v[130:133], v[122:125]
	v_mfma_f32_16x16x32_bf16 v[118:121], v[170:173], v[130:133], v[118:121]
	v_mfma_f32_16x16x32_bf16 v[114:117], v[174:177], v[130:133], v[114:117]
	v_mfma_f32_16x16x32_bf16 v[110:113], v[162:165], v[134:137], v[110:113]
	v_mfma_f32_16x16x32_bf16 v[106:109], v[166:169], v[134:137], v[106:109]
	v_mfma_f32_16x16x32_bf16 v[102:105], v[170:173], v[134:137], v[102:105]
	v_mfma_f32_16x16x32_bf16 v[98:101], v[174:177], v[134:137], v[98:101]
	v_mfma_f32_16x16x32_bf16 v[94:97], v[162:165], v[138:141], v[94:97]
	v_mfma_f32_16x16x32_bf16 v[90:93], v[166:169], v[138:141], v[90:93]
	v_mfma_f32_16x16x32_bf16 v[86:89], v[170:173], v[138:141], v[86:89]
	v_mfma_f32_16x16x32_bf16 v[82:85], v[174:177], v[138:141], v[82:85]
	v_mfma_f32_16x16x32_bf16 v[78:81], v[162:165], v[142:145], v[78:81]
	v_mfma_f32_16x16x32_bf16 v[74:77], v[166:169], v[142:145], v[74:77]
	v_mfma_f32_16x16x32_bf16 v[70:73], v[170:173], v[142:145], v[70:73]
	v_mfma_f32_16x16x32_bf16 v[66:69], v[174:177], v[142:145], v[66:69]
	ds_read_b128 v[130:133], v248 offset:8192
	ds_read_b128 v[134:137], v248 offset:10240
	ds_read_b128 v[138:141], v248 offset:12288
	ds_read_b128 v[142:145], v248 offset:14336
	v_mfma_f32_16x16x32_bf16 v[62:65], v[162:165], v[146:149], v[62:65]
	v_mfma_f32_16x16x32_bf16 v[58:61], v[166:169], v[146:149], v[58:61]
	v_mfma_f32_16x16x32_bf16 v[54:57], v[170:173], v[146:149], v[54:57]
	v_mfma_f32_16x16x32_bf16 v[50:53], v[174:177], v[146:149], v[50:53]
	v_mfma_f32_16x16x32_bf16 v[46:49], v[162:165], v[150:153], v[46:49]
	v_mfma_f32_16x16x32_bf16 v[42:45], v[166:169], v[150:153], v[42:45]
	v_mfma_f32_16x16x32_bf16 v[38:41], v[170:173], v[150:153], v[38:41]
	v_mfma_f32_16x16x32_bf16 v[34:37], v[174:177], v[150:153], v[34:37]
	v_mfma_f32_16x16x32_bf16 v[30:33], v[162:165], v[154:157], v[30:33]
	v_mfma_f32_16x16x32_bf16 v[26:29], v[166:169], v[154:157], v[26:29]
	v_mfma_f32_16x16x32_bf16 v[22:25], v[170:173], v[154:157], v[22:25]
	v_mfma_f32_16x16x32_bf16 v[18:21], v[174:177], v[154:157], v[18:21]
	v_mfma_f32_16x16x32_bf16 v[14:17], v[162:165], v[158:161], v[14:17]
	v_mfma_f32_16x16x32_bf16 v[10:13], v[166:169], v[158:161], v[10:13]
	v_mfma_f32_16x16x32_bf16 v[6:9], v[170:173], v[158:161], v[6:9]
	v_mfma_f32_16x16x32_bf16 v[2:5], v[174:177], v[158:161], v[2:5]
	s_waitcnt lgkmcnt(0)
	v_mfma_f32_16x16x32_bf16 v[62:65], v[178:181], v[130:133], v[62:65]
	v_mfma_f32_16x16x32_bf16 v[58:61], v[182:185], v[130:133], v[58:61]
	v_mfma_f32_16x16x32_bf16 v[54:57], v[186:189], v[130:133], v[54:57]
	v_mfma_f32_16x16x32_bf16 v[50:53], v[190:193], v[130:133], v[50:53]
	v_mfma_f32_16x16x32_bf16 v[46:49], v[178:181], v[134:137], v[46:49]
	v_mfma_f32_16x16x32_bf16 v[42:45], v[182:185], v[134:137], v[42:45]
	v_mfma_f32_16x16x32_bf16 v[38:41], v[186:189], v[134:137], v[38:41]
	v_mfma_f32_16x16x32_bf16 v[34:37], v[190:193], v[134:137], v[34:37]
	v_mfma_f32_16x16x32_bf16 v[30:33], v[178:181], v[138:141], v[30:33]
	v_mfma_f32_16x16x32_bf16 v[26:29], v[182:185], v[138:141], v[26:29]
	v_mfma_f32_16x16x32_bf16 v[22:25], v[186:189], v[138:141], v[22:25]
	v_mfma_f32_16x16x32_bf16 v[18:21], v[190:193], v[138:141], v[18:21]
	v_mfma_f32_16x16x32_bf16 v[14:17], v[178:181], v[142:145], v[14:17]
	v_mfma_f32_16x16x32_bf16 v[10:13], v[182:185], v[142:145], v[10:13]
	v_mfma_f32_16x16x32_bf16 v[6:9], v[186:189], v[142:145], v[6:9]
	v_mfma_f32_16x16x32_bf16 v[2:5], v[190:193], v[142:145], v[2:5]
	v_mfma_f32_16x16x32_bf16 v[126:129], v[178:181], v[232:235], v[126:129]
	v_mfma_f32_16x16x32_bf16 v[122:125], v[182:185], v[232:235], v[122:125]
	v_mfma_f32_16x16x32_bf16 v[118:121], v[186:189], v[232:235], v[118:121]
	v_mfma_f32_16x16x32_bf16 v[114:117], v[190:193], v[232:235], v[114:117]
	v_mfma_f32_16x16x32_bf16 v[110:113], v[178:181], v[236:239], v[110:113]
	v_mfma_f32_16x16x32_bf16 v[106:109], v[182:185], v[236:239], v[106:109]
	v_mfma_f32_16x16x32_bf16 v[102:105], v[186:189], v[236:239], v[102:105]
	v_mfma_f32_16x16x32_bf16 v[98:101], v[190:193], v[236:239], v[98:101]
	v_mfma_f32_16x16x32_bf16 v[94:97], v[178:181], v[240:243], v[94:97]
	v_mfma_f32_16x16x32_bf16 v[90:93], v[182:185], v[240:243], v[90:93]
	v_mfma_f32_16x16x32_bf16 v[86:89], v[186:189], v[240:243], v[86:89]
	v_mfma_f32_16x16x32_bf16 v[82:85], v[190:193], v[240:243], v[82:85]
	v_mfma_f32_16x16x32_bf16 v[78:81], v[178:181], v[244:247], v[78:81]
	v_mfma_f32_16x16x32_bf16 v[74:77], v[182:185], v[244:247], v[74:77]
	v_mfma_f32_16x16x32_bf16 v[70:73], v[186:189], v[244:247], v[70:73]
	v_mfma_f32_16x16x32_bf16 v[66:69], v[190:193], v[244:247], v[66:69]

.LBB0_797:
	v_lshlrev_b32_e32 v130, 7, v212
	v_ashrrev_i32_e32 v131, 31, v130
	s_lshl_b64 s[0:1], s[0:1], 8
	v_lshl_add_u64 v[134:135], s[0:1], 0, v[130:131]
	v_or_b32_e32 v134, v134, v205
	v_mov_b64_e32 v[130:131], s[92:93]
	v_mad_u64_u32 v[132:133], s[0:1], v134, s33, v[130:131]
	s_lshl_b32 s0, s8, 8
	s_nop 0
	v_lshl_or_b32 v1, v1, 6, s0
	v_mad_i32_i24 v133, v135, s33, v133
	v_lshl_or_b32 v130, v204, 3, v1
	v_mov_b32_e32 v131, v0
	v_lshl_add_u64 v[132:133], v[132:133], 0, v[130:131]
	s_movk_i32 s0, 0x2000
	v_add_co_u32_e32 v136, vcc, s0, v132
	v_mul_f32_e32 v1, 0xbfb8aa3b, v126
	s_nop 0
	v_addc_co_u32_e32 v137, vcc, 0, v133, vcc
	global_load_dwordx2 v[136:137], v[136:137], off offset:2048
	v_mul_f32_e32 v126, 0xbfb8aa3b, v127
	v_mul_f32_e32 v127, 0xbfb8aa3b, v128
	v_mul_f32_e32 v128, 0xbfb8aa3b, v129
	v_exp_f32_e32 v1, v1
	v_exp_f32_e32 v138, v126
	v_exp_f32_e32 v139, v127
	v_exp_f32_e32 v140, v128
	v_lshlrev_b64 v[126:127], 12, v[134:135]
	v_add_f32_e32 v1, 1.0, v1
	v_add_f32_e32 v135, 1.0, v138
	v_add_f32_e32 v138, 1.0, v139
	v_add_f32_e32 v139, 1.0, v140
	v_rcp_f32_e32 v134, v1
	v_rcp_f32_e32 v135, v135
	v_rcp_f32_e32 v138, v138
	v_rcp_f32_e32 v139, v139
	v_lshl_add_u64 v[128:129], s[94:95], 0, v[126:127]
	v_pk_mul_f32 v[122:123], v[122:123], v[134:135]
	v_lshl_add_u64 v[128:129], v[128:129], 0, v[130:131]
	v_pk_mul_f32 v[124:125], v[124:125], v[138:139]
	s_mov_b64 s[0:1], 0x2800
	v_lshl_add_u64 v[140:141], v[132:133], 0, s[0:1]
	v_mul_f32_e32 v1, 0xbfb8aa3b, v118
	v_mul_f32_e32 v118, 0xbfb8aa3b, v119
	v_mul_f32_e32 v119, 0xbfb8aa3b, v120
	v_mul_f32_e32 v120, 0xbfb8aa3b, v121
	v_exp_f32_e32 v1, v1
	v_exp_f32_e32 v118, v118
	v_exp_f32_e32 v119, v119
	v_exp_f32_e32 v120, v120
	v_add_f32_e32 v1, 1.0, v1
	v_add_f32_e32 v121, 1.0, v118
	v_rcp_f32_e32 v118, v1
	s_mov_b32 s0, 0x32000
	v_mul_f32_e32 v1, 0xbfb8aa3b, v110
	v_mul_f32_e32 v110, 0xbfb8aa3b, v111
	v_mul_f32_e32 v111, 0xbfb8aa3b, v112
	v_mul_f32_e32 v112, 0xbfb8aa3b, v113
	v_exp_f32_e32 v1, v1
	v_exp_f32_e32 v113, v110
	v_exp_f32_e32 v112, v112
	v_or_b32_e32 v110, 0x10000, v126
	v_add_f32_e32 v1, 1.0, v1
	v_add_f32_e32 v113, 1.0, v113
	v_rcp_f32_e32 v113, v113
	s_add_i32 s30, s30, s34
	s_waitcnt vmcnt(0)
	v_lshlrev_b32_e32 v134, 16, v136
	v_and_b32_e32 v135, 0xffff0000, v136
	v_lshlrev_b32_e32 v136, 16, v137
	v_and_b32_e32 v137, 0xffff0000, v137
	v_pk_mul_f32 v[122:123], v[122:123], v[134:135]
	v_pk_mul_f32 v[124:125], v[124:125], v[136:137]
	v_cvt_pk_bf16_f32 v122, v122, v123
	v_cvt_pk_bf16_f32 v123, v124, v125
	global_store_dwordx2 v[128:129], v[122:123], off offset:2048
	global_load_dwordx2 v[122:123], v[140:141], off offset:32
	v_add_f32_e32 v124, 1.0, v119
	v_add_f32_e32 v125, 1.0, v120
	v_rcp_f32_e32 v119, v121
	v_rcp_f32_e32 v120, v124
	v_rcp_f32_e32 v121, v125
	v_add_co_u32_e32 v124, vcc, s0, v132
	v_pk_mul_f32 v[114:115], v[114:115], v[118:119]
	v_pk_mul_f32 v[116:117], v[116:117], v[120:121]
	v_addc_co_u32_e32 v125, vcc, 0, v133, vcc
	s_mov_b64 s[0:1], 0x32800
	s_waitcnt vmcnt(0)
	v_lshlrev_b32_e32 v118, 16, v122
	v_and_b32_e32 v119, 0xffff0000, v122
	v_lshlrev_b32_e32 v120, 16, v123
	v_and_b32_e32 v121, 0xffff0000, v123
	v_pk_mul_f32 v[114:115], v[114:115], v[118:119]
	v_pk_mul_f32 v[116:117], v[116:117], v[120:121]
	v_cvt_pk_bf16_f32 v114, v114, v115
	v_cvt_pk_bf16_f32 v115, v116, v117
	global_store_dwordx2 v[128:129], v[114:115], off offset:2080
	global_load_dwordx2 v[114:115], v[124:125], off offset:2048
	v_exp_f32_e32 v116, v111
	v_add_f32_e32 v117, 1.0, v112
	v_rcp_f32_e32 v112, v1
	v_rcp_f32_e32 v117, v117
	v_add_f32_e32 v116, 1.0, v116
	v_rcp_f32_e32 v116, v116
	v_mov_b32_e32 v111, v127
	v_pk_mul_f32 v[106:107], v[106:107], v[112:113]
	v_lshl_add_u64 v[110:111], s[94:95], 0, v[110:111]
	v_pk_mul_f32 v[108:109], v[108:109], v[116:117]
	v_lshl_add_u64 v[110:111], v[110:111], 0, v[130:131]
	v_lshl_add_u64 v[118:119], v[132:133], 0, s[0:1]
	v_mul_f32_e32 v1, 0xbfb8aa3b, v102
	v_mul_f32_e32 v102, 0xbfb8aa3b, v103
	v_mul_f32_e32 v103, 0xbfb8aa3b, v104
	v_mul_f32_e32 v104, 0xbfb8aa3b, v105
	v_exp_f32_e32 v1, v1
	v_exp_f32_e32 v102, v102
	v_exp_f32_e32 v103, v103
	v_exp_f32_e32 v104, v104
	v_add_f32_e32 v1, 1.0, v1
	v_add_f32_e32 v105, 1.0, v102
	v_rcp_f32_e32 v102, v1
	s_mov_b32 s0, 0x62000
	v_mul_f32_e32 v1, 0xbfb8aa3b, v94
	v_mul_f32_e32 v94, 0xbfb8aa3b, v95
	v_mul_f32_e32 v95, 0xbfb8aa3b, v96
	v_mul_f32_e32 v96, 0xbfb8aa3b, v97
	v_exp_f32_e32 v1, v1
	v_exp_f32_e32 v97, v94
	v_exp_f32_e32 v96, v96
	v_or_b32_e32 v94, 0x20000, v126
	v_add_f32_e32 v1, 1.0, v1
	v_add_f32_e32 v97, 1.0, v97
	v_rcp_f32_e32 v97, v97
	s_waitcnt vmcnt(0)
	v_lshlrev_b32_e32 v112, 16, v114
	v_and_b32_e32 v113, 0xffff0000, v114
	v_lshlrev_b32_e32 v114, 16, v115
	v_and_b32_e32 v115, 0xffff0000, v115
	v_pk_mul_f32 v[106:107], v[106:107], v[112:113]
	v_pk_mul_f32 v[108:109], v[108:109], v[114:115]
	v_cvt_pk_bf16_f32 v106, v106, v107
	v_cvt_pk_bf16_f32 v107, v108, v109
	global_store_dwordx2 v[110:111], v[106:107], off offset:2048
	global_load_dwordx2 v[106:107], v[118:119], off offset:32
	v_add_f32_e32 v108, 1.0, v103
	v_add_f32_e32 v109, 1.0, v104
	v_rcp_f32_e32 v103, v105
	v_rcp_f32_e32 v104, v108
	v_rcp_f32_e32 v105, v109
	v_add_co_u32_e32 v108, vcc, s0, v132
	v_pk_mul_f32 v[98:99], v[98:99], v[102:103]
	v_pk_mul_f32 v[100:101], v[100:101], v[104:105]
	v_addc_co_u32_e32 v109, vcc, 0, v133, vcc
	s_mov_b64 s[0:1], 0x62800
	s_waitcnt vmcnt(0)
	v_lshlrev_b32_e32 v102, 16, v106
	v_and_b32_e32 v103, 0xffff0000, v106
	v_lshlrev_b32_e32 v104, 16, v107
	v_and_b32_e32 v105, 0xffff0000, v107
	v_pk_mul_f32 v[98:99], v[98:99], v[102:103]
	v_pk_mul_f32 v[100:101], v[100:101], v[104:105]
	v_cvt_pk_bf16_f32 v98, v98, v99
	v_cvt_pk_bf16_f32 v99, v100, v101
	global_store_dwordx2 v[110:111], v[98:99], off offset:2080
	global_load_dwordx2 v[98:99], v[108:109], off offset:2048
	v_exp_f32_e32 v100, v95
	v_add_f32_e32 v101, 1.0, v96
	v_rcp_f32_e32 v96, v1
	v_rcp_f32_e32 v101, v101
	v_add_f32_e32 v100, 1.0, v100
	v_rcp_f32_e32 v100, v100
	v_mov_b32_e32 v95, v127
	v_pk_mul_f32 v[90:91], v[90:91], v[96:97]
	v_lshl_add_u64 v[94:95], s[94:95], 0, v[94:95]
	v_pk_mul_f32 v[92:93], v[92:93], v[100:101]
	v_lshl_add_u64 v[94:95], v[94:95], 0, v[130:131]
	v_lshl_add_u64 v[102:103], v[132:133], 0, s[0:1]
	v_mul_f32_e32 v1, 0xbfb8aa3b, v86
	v_mul_f32_e32 v86, 0xbfb8aa3b, v87
	v_mul_f32_e32 v87, 0xbfb8aa3b, v88
	v_mul_f32_e32 v88, 0xbfb8aa3b, v89
	v_exp_f32_e32 v1, v1
	v_exp_f32_e32 v86, v86
	v_exp_f32_e32 v87, v87
	v_exp_f32_e32 v88, v88
	v_add_f32_e32 v1, 1.0, v1
	v_add_f32_e32 v89, 1.0, v86
	v_rcp_f32_e32 v86, v1
	s_mov_b32 s0, 0x92000
	v_mul_f32_e32 v1, 0xbfb8aa3b, v78
	v_mul_f32_e32 v78, 0xbfb8aa3b, v79
	v_mul_f32_e32 v79, 0xbfb8aa3b, v80
	v_mul_f32_e32 v80, 0xbfb8aa3b, v81
	v_exp_f32_e32 v1, v1
	v_exp_f32_e32 v81, v78
	v_exp_f32_e32 v80, v80
	v_or_b32_e32 v78, 0x30000, v126
	v_add_f32_e32 v1, 1.0, v1
	v_add_f32_e32 v81, 1.0, v81
	v_rcp_f32_e32 v81, v81
	s_waitcnt vmcnt(0)
	v_lshlrev_b32_e32 v96, 16, v98
	v_and_b32_e32 v97, 0xffff0000, v98
	v_lshlrev_b32_e32 v98, 16, v99
	v_and_b32_e32 v99, 0xffff0000, v99
	v_pk_mul_f32 v[90:91], v[90:91], v[96:97]
	v_pk_mul_f32 v[92:93], v[92:93], v[98:99]
	v_cvt_pk_bf16_f32 v90, v90, v91
	v_cvt_pk_bf16_f32 v91, v92, v93
	global_store_dwordx2 v[94:95], v[90:91], off offset:2048
	global_load_dwordx2 v[90:91], v[102:103], off offset:32
	v_add_f32_e32 v92, 1.0, v87
	v_add_f32_e32 v93, 1.0, v88
	v_rcp_f32_e32 v87, v89
	v_rcp_f32_e32 v88, v92
	v_rcp_f32_e32 v89, v93
	v_add_co_u32_e32 v92, vcc, s0, v132
	v_pk_mul_f32 v[82:83], v[82:83], v[86:87]
	v_pk_mul_f32 v[84:85], v[84:85], v[88:89]
	v_addc_co_u32_e32 v93, vcc, 0, v133, vcc
	s_mov_b64 s[0:1], 0x92800
	s_waitcnt vmcnt(0)
	v_lshlrev_b32_e32 v86, 16, v90
	v_and_b32_e32 v87, 0xffff0000, v90
	v_lshlrev_b32_e32 v88, 16, v91
	v_and_b32_e32 v89, 0xffff0000, v91
	v_pk_mul_f32 v[82:83], v[82:83], v[86:87]
	v_pk_mul_f32 v[84:85], v[84:85], v[88:89]
	v_cvt_pk_bf16_f32 v82, v82, v83
	v_cvt_pk_bf16_f32 v83, v84, v85
	global_store_dwordx2 v[94:95], v[82:83], off offset:2080
	global_load_dwordx2 v[82:83], v[92:93], off offset:2048
	v_exp_f32_e32 v84, v79
	v_add_f32_e32 v85, 1.0, v80
	v_rcp_f32_e32 v80, v1
	v_rcp_f32_e32 v85, v85
	v_add_f32_e32 v84, 1.0, v84
	v_rcp_f32_e32 v84, v84
	v_mov_b32_e32 v79, v127
	v_pk_mul_f32 v[74:75], v[74:75], v[80:81]
	v_lshl_add_u64 v[78:79], s[94:95], 0, v[78:79]
	v_pk_mul_f32 v[76:77], v[76:77], v[84:85]
	v_lshl_add_u64 v[78:79], v[78:79], 0, v[130:131]
	v_lshl_add_u64 v[86:87], v[132:133], 0, s[0:1]
	v_mul_f32_e32 v1, 0xbfb8aa3b, v70
	v_mul_f32_e32 v70, 0xbfb8aa3b, v71
	v_mul_f32_e32 v71, 0xbfb8aa3b, v72
	v_mul_f32_e32 v72, 0xbfb8aa3b, v73
	v_exp_f32_e32 v1, v1
	v_exp_f32_e32 v70, v70
	v_exp_f32_e32 v71, v71
	v_exp_f32_e32 v72, v72
	v_add_f32_e32 v1, 1.0, v1
	v_add_f32_e32 v73, 1.0, v70
	v_rcp_f32_e32 v70, v1
	s_mov_b32 s0, 0xc2000
	v_mul_f32_e32 v1, 0xbfb8aa3b, v62
	v_mul_f32_e32 v62, 0xbfb8aa3b, v63
	v_mul_f32_e32 v63, 0xbfb8aa3b, v64
	v_mul_f32_e32 v64, 0xbfb8aa3b, v65
	v_exp_f32_e32 v1, v1
	v_exp_f32_e32 v65, v62
	v_exp_f32_e32 v64, v64
	v_or_b32_e32 v62, 0x40000, v126
	v_add_f32_e32 v1, 1.0, v1
	v_add_f32_e32 v65, 1.0, v65
	v_rcp_f32_e32 v65, v65
	s_waitcnt vmcnt(0)
	v_lshlrev_b32_e32 v80, 16, v82
	v_and_b32_e32 v81, 0xffff0000, v82
	v_lshlrev_b32_e32 v82, 16, v83
	v_and_b32_e32 v83, 0xffff0000, v83
	v_pk_mul_f32 v[74:75], v[74:75], v[80:81]
	v_pk_mul_f32 v[76:77], v[76:77], v[82:83]
	v_cvt_pk_bf16_f32 v74, v74, v75
	v_cvt_pk_bf16_f32 v75, v76, v77
	global_store_dwordx2 v[78:79], v[74:75], off offset:2048
	global_load_dwordx2 v[74:75], v[86:87], off offset:32
	v_add_f32_e32 v76, 1.0, v71
	v_add_f32_e32 v77, 1.0, v72
	v_rcp_f32_e32 v71, v73
	v_rcp_f32_e32 v72, v76
	v_rcp_f32_e32 v73, v77
	v_add_co_u32_e32 v76, vcc, s0, v132
	v_pk_mul_f32 v[66:67], v[66:67], v[70:71]
	v_pk_mul_f32 v[68:69], v[68:69], v[72:73]
	v_addc_co_u32_e32 v77, vcc, 0, v133, vcc
	s_mov_b64 s[0:1], 0xc2800
	s_waitcnt vmcnt(0)
	v_lshlrev_b32_e32 v70, 16, v74
	v_and_b32_e32 v71, 0xffff0000, v74
	v_lshlrev_b32_e32 v72, 16, v75
	v_and_b32_e32 v73, 0xffff0000, v75
	v_pk_mul_f32 v[66:67], v[66:67], v[70:71]
	v_pk_mul_f32 v[68:69], v[68:69], v[72:73]
	v_cvt_pk_bf16_f32 v66, v66, v67
	v_cvt_pk_bf16_f32 v67, v68, v69
	global_store_dwordx2 v[78:79], v[66:67], off offset:2080
	global_load_dwordx2 v[66:67], v[76:77], off offset:2048
	v_exp_f32_e32 v68, v63
	v_add_f32_e32 v69, 1.0, v64
	v_rcp_f32_e32 v64, v1
	v_rcp_f32_e32 v69, v69
	v_add_f32_e32 v68, 1.0, v68
	v_rcp_f32_e32 v68, v68
	v_mov_b32_e32 v63, v127
	v_pk_mul_f32 v[58:59], v[58:59], v[64:65]
	v_lshl_add_u64 v[62:63], s[94:95], 0, v[62:63]
	v_pk_mul_f32 v[60:61], v[60:61], v[68:69]
	v_lshl_add_u64 v[62:63], v[62:63], 0, v[130:131]
	v_lshl_add_u64 v[70:71], v[132:133], 0, s[0:1]
	v_mul_f32_e32 v1, 0xbfb8aa3b, v54
	v_mul_f32_e32 v54, 0xbfb8aa3b, v55
	v_mul_f32_e32 v55, 0xbfb8aa3b, v56
	v_mul_f32_e32 v56, 0xbfb8aa3b, v57
	v_exp_f32_e32 v1, v1
	v_exp_f32_e32 v54, v54
	v_exp_f32_e32 v55, v55
	v_exp_f32_e32 v56, v56
	v_add_f32_e32 v1, 1.0, v1
	v_add_f32_e32 v57, 1.0, v54
	v_rcp_f32_e32 v54, v1
	s_mov_b32 s0, 0xf2000
	v_mul_f32_e32 v1, 0xbfb8aa3b, v46
	v_mul_f32_e32 v46, 0xbfb8aa3b, v47
	v_mul_f32_e32 v47, 0xbfb8aa3b, v48
	v_mul_f32_e32 v48, 0xbfb8aa3b, v49
	v_exp_f32_e32 v1, v1
	v_exp_f32_e32 v49, v46
	v_exp_f32_e32 v48, v48
	v_or_b32_e32 v46, 0x50000, v126
	v_add_f32_e32 v1, 1.0, v1
	v_add_f32_e32 v49, 1.0, v49
	v_rcp_f32_e32 v49, v49
	s_waitcnt vmcnt(0)
	v_lshlrev_b32_e32 v64, 16, v66
	v_and_b32_e32 v65, 0xffff0000, v66
	v_lshlrev_b32_e32 v66, 16, v67
	v_and_b32_e32 v67, 0xffff0000, v67
	v_pk_mul_f32 v[58:59], v[58:59], v[64:65]
	v_pk_mul_f32 v[60:61], v[60:61], v[66:67]
	v_cvt_pk_bf16_f32 v58, v58, v59
	v_cvt_pk_bf16_f32 v59, v60, v61
	global_store_dwordx2 v[62:63], v[58:59], off offset:2048
	global_load_dwordx2 v[58:59], v[70:71], off offset:32
	v_add_f32_e32 v60, 1.0, v55
	v_add_f32_e32 v61, 1.0, v56
	v_rcp_f32_e32 v55, v57
	v_rcp_f32_e32 v56, v60
	v_rcp_f32_e32 v57, v61
	v_add_co_u32_e32 v60, vcc, s0, v132
	v_pk_mul_f32 v[50:51], v[50:51], v[54:55]
	v_pk_mul_f32 v[52:53], v[52:53], v[56:57]
	v_addc_co_u32_e32 v61, vcc, 0, v133, vcc
	s_mov_b64 s[0:1], 0xf2800
	s_waitcnt vmcnt(0)
	v_lshlrev_b32_e32 v54, 16, v58
	v_and_b32_e32 v55, 0xffff0000, v58
	v_lshlrev_b32_e32 v56, 16, v59
	v_and_b32_e32 v57, 0xffff0000, v59
	v_pk_mul_f32 v[50:51], v[50:51], v[54:55]
	v_pk_mul_f32 v[52:53], v[52:53], v[56:57]
	v_cvt_pk_bf16_f32 v50, v50, v51
	v_cvt_pk_bf16_f32 v51, v52, v53
	global_store_dwordx2 v[62:63], v[50:51], off offset:2080
	global_load_dwordx2 v[50:51], v[60:61], off offset:2048
	v_exp_f32_e32 v52, v47
	v_add_f32_e32 v53, 1.0, v48
	v_rcp_f32_e32 v48, v1
	v_rcp_f32_e32 v53, v53
	v_add_f32_e32 v52, 1.0, v52
	v_rcp_f32_e32 v52, v52
	v_mov_b32_e32 v47, v127
	v_pk_mul_f32 v[42:43], v[42:43], v[48:49]
	v_lshl_add_u64 v[46:47], s[94:95], 0, v[46:47]
	v_pk_mul_f32 v[44:45], v[44:45], v[52:53]
	v_lshl_add_u64 v[46:47], v[46:47], 0, v[130:131]
	v_lshl_add_u64 v[54:55], v[132:133], 0, s[0:1]
	v_mul_f32_e32 v1, 0xbfb8aa3b, v38
	v_mul_f32_e32 v38, 0xbfb8aa3b, v39
	v_mul_f32_e32 v39, 0xbfb8aa3b, v40
	v_mul_f32_e32 v40, 0xbfb8aa3b, v41
	v_exp_f32_e32 v1, v1
	v_exp_f32_e32 v38, v38
	v_exp_f32_e32 v39, v39
	v_exp_f32_e32 v40, v40
	v_add_f32_e32 v1, 1.0, v1
	v_add_f32_e32 v41, 1.0, v38
	v_rcp_f32_e32 v38, v1
	s_mov_b32 s0, 0x122000
	v_mul_f32_e32 v1, 0xbfb8aa3b, v34
	v_mul_f32_e32 v34, 0xbfb8aa3b, v37
	v_exp_f32_e32 v1, v1
	v_exp_f32_e32 v34, v34
	v_add_f32_e32 v1, 1.0, v1
	v_add_f32_e32 v37, 1.0, v34
	v_rcp_f32_e32 v34, v1
	v_rcp_f32_e32 v37, v37
	v_mul_f32_e32 v1, 0xbfb8aa3b, v22
	v_mul_f32_e32 v22, 0xbfb8aa3b, v23
	v_mul_f32_e32 v23, 0xbfb8aa3b, v24
	v_mul_f32_e32 v24, 0xbfb8aa3b, v25
	v_exp_f32_e32 v1, v1
	v_exp_f32_e32 v22, v22
	v_exp_f32_e32 v23, v23
	v_exp_f32_e32 v24, v24
	v_add_f32_e32 v1, 1.0, v1
	v_add_f32_e32 v25, 1.0, v22
	v_rcp_f32_e32 v22, v1
	v_mul_f32_e32 v1, 0xbfb8aa3b, v10
	v_mul_f32_e32 v10, 0xbfb8aa3b, v11
	v_mul_f32_e32 v11, 0xbfb8aa3b, v12
	v_mul_f32_e32 v12, 0xbfb8aa3b, v13
	v_exp_f32_e32 v1, v1
	v_exp_f32_e32 v10, v10
	v_exp_f32_e32 v11, v11
	v_exp_f32_e32 v12, v12
	v_add_f32_e32 v1, 1.0, v1
	v_add_f32_e32 v13, 1.0, v10
	v_rcp_f32_e32 v13, v13
	s_waitcnt vmcnt(0)
	v_lshlrev_b32_e32 v48, 16, v50
	v_and_b32_e32 v49, 0xffff0000, v50
	v_lshlrev_b32_e32 v50, 16, v51
	v_and_b32_e32 v51, 0xffff0000, v51
	v_pk_mul_f32 v[42:43], v[42:43], v[48:49]
	v_pk_mul_f32 v[44:45], v[44:45], v[50:51]
	v_cvt_pk_bf16_f32 v42, v42, v43
	v_cvt_pk_bf16_f32 v43, v44, v45
	global_store_dwordx2 v[46:47], v[42:43], off offset:2048
	global_load_dwordx2 v[42:43], v[54:55], off offset:32
	v_add_f32_e32 v44, 1.0, v39
	v_add_f32_e32 v45, 1.0, v40
	v_rcp_f32_e32 v39, v41
	v_rcp_f32_e32 v40, v44
	v_rcp_f32_e32 v41, v45
	v_add_co_u32_e32 v44, vcc, s0, v132
	v_pk_mul_f32 v[30:31], v[30:31], v[38:39]
	v_pk_mul_f32 v[32:33], v[32:33], v[40:41]
	v_addc_co_u32_e32 v45, vcc, 0, v133, vcc
	s_mov_b64 s[0:1], 0x122800
	s_waitcnt vmcnt(0)
	v_lshlrev_b32_e32 v38, 16, v42
	v_and_b32_e32 v39, 0xffff0000, v42
	v_lshlrev_b32_e32 v40, 16, v43
	v_and_b32_e32 v41, 0xffff0000, v43
	v_pk_mul_f32 v[30:31], v[30:31], v[38:39]
	v_pk_mul_f32 v[32:33], v[32:33], v[40:41]
	v_cvt_pk_bf16_f32 v30, v30, v31
	v_cvt_pk_bf16_f32 v31, v32, v33
	global_store_dwordx2 v[46:47], v[30:31], off offset:2080
	global_load_dwordx2 v[30:31], v[44:45], off offset:2048
	v_mul_f32_e32 v32, 0xbfb8aa3b, v35
	v_mul_f32_e32 v33, 0xbfb8aa3b, v36
	v_exp_f32_e32 v35, v32
	v_exp_f32_e32 v36, v33
	v_or_b32_e32 v32, 0x60000, v126
	v_mov_b32_e32 v33, v127
	v_add_f32_e32 v35, 1.0, v35
	v_add_f32_e32 v36, 1.0, v36
	v_rcp_f32_e32 v35, v35
	v_rcp_f32_e32 v36, v36
	v_lshl_add_u64 v[32:33], s[94:95], 0, v[32:33]
	v_lshl_add_u64 v[32:33], v[32:33], 0, v[130:131]
	v_pk_mul_f32 v[26:27], v[26:27], v[34:35]
	v_pk_mul_f32 v[28:29], v[28:29], v[36:37]
	v_lshl_add_u64 v[38:39], v[132:133], 0, s[0:1]
	s_mov_b32 s0, 0x152000
	v_or_b32_e32 v126, 0x70000, v126
	s_waitcnt vmcnt(0)
	v_lshlrev_b32_e32 v34, 16, v30
	v_and_b32_e32 v35, 0xffff0000, v30
	v_lshlrev_b32_e32 v30, 16, v31
	v_and_b32_e32 v31, 0xffff0000, v31
	v_pk_mul_f32 v[26:27], v[26:27], v[34:35]
	v_pk_mul_f32 v[28:29], v[28:29], v[30:31]
	v_cvt_pk_bf16_f32 v26, v26, v27
	v_cvt_pk_bf16_f32 v27, v28, v29
	global_store_dwordx2 v[32:33], v[26:27], off offset:2048
	global_load_dwordx2 v[26:27], v[38:39], off offset:32
	v_add_f32_e32 v28, 1.0, v23
	v_add_f32_e32 v29, 1.0, v24
	v_rcp_f32_e32 v23, v25
	v_rcp_f32_e32 v24, v28
	v_rcp_f32_e32 v25, v29
	v_add_co_u32_e32 v28, vcc, s0, v132
	v_pk_mul_f32 v[14:15], v[14:15], v[22:23]
	v_pk_mul_f32 v[16:17], v[16:17], v[24:25]
	v_addc_co_u32_e32 v29, vcc, 0, v133, vcc
	s_mov_b64 s[0:1], 0x152800
	s_waitcnt vmcnt(0)
	v_lshlrev_b32_e32 v22, 16, v26
	v_and_b32_e32 v23, 0xffff0000, v26
	v_lshlrev_b32_e32 v24, 16, v27
	v_and_b32_e32 v25, 0xffff0000, v27
	v_pk_mul_f32 v[14:15], v[14:15], v[22:23]
	v_pk_mul_f32 v[16:17], v[16:17], v[24:25]
	v_cvt_pk_bf16_f32 v14, v14, v15
	v_cvt_pk_bf16_f32 v15, v16, v17
	global_store_dwordx2 v[32:33], v[14:15], off offset:2080
	global_load_dwordx2 v[14:15], v[28:29], off offset:2048
	v_add_f32_e32 v16, 1.0, v11
	v_add_f32_e32 v17, 1.0, v12
	v_rcp_f32_e32 v12, v1
	v_rcp_f32_e32 v16, v16
	v_rcp_f32_e32 v17, v17
	v_lshl_add_u64 v[10:11], s[94:95], 0, v[126:127]
	v_pk_mul_f32 v[6:7], v[6:7], v[12:13]
	v_lshl_add_u64 v[10:11], v[10:11], 0, v[130:131]
	v_pk_mul_f32 v[8:9], v[8:9], v[16:17]
	v_lshl_add_u64 v[22:23], v[132:133], 0, s[0:1]
	v_mul_f32_e32 v1, 0xbfb8aa3b, v18
	v_exp_f32_e32 v1, v1
	v_readlane_b32 s0, v229, 39
	s_add_i32 s29, s29, s0
	s_cmpk_gt_i32 s30, 0x1ff
	v_add_f32_e32 v1, 1.0, v1
	s_waitcnt vmcnt(0)
	v_lshlrev_b32_e32 v12, 16, v14
	v_and_b32_e32 v13, 0xffff0000, v14
	v_lshlrev_b32_e32 v14, 16, v15
	v_and_b32_e32 v15, 0xffff0000, v15
	v_pk_mul_f32 v[6:7], v[6:7], v[12:13]
	v_pk_mul_f32 v[8:9], v[8:9], v[14:15]
	v_cvt_pk_bf16_f32 v6, v6, v7
	v_cvt_pk_bf16_f32 v7, v8, v9
	global_store_dwordx2 v[10:11], v[6:7], off offset:2048
	global_load_dwordx2 v[6:7], v[22:23], off offset:32
	v_mul_f32_e32 v8, 0xbfb8aa3b, v19
	v_mul_f32_e32 v9, 0xbfb8aa3b, v20
	v_mul_f32_e32 v12, 0xbfb8aa3b, v21
	v_exp_f32_e32 v8, v8
	v_exp_f32_e32 v9, v9
	v_exp_f32_e32 v12, v12
	v_add_f32_e32 v13, 1.0, v8
	v_add_f32_e32 v14, 1.0, v9
	v_add_f32_e32 v15, 1.0, v12
	v_rcp_f32_e32 v8, v1
	v_rcp_f32_e32 v9, v13
	v_rcp_f32_e32 v12, v14
	v_rcp_f32_e32 v13, v15
	v_pk_mul_f32 v[2:3], v[2:3], v[8:9]
	v_pk_mul_f32 v[4:5], v[4:5], v[12:13]
	s_waitcnt vmcnt(0)
	v_lshlrev_b32_e32 v8, 16, v6
	v_and_b32_e32 v9, 0xffff0000, v6
	v_lshlrev_b32_e32 v6, 16, v7
	v_and_b32_e32 v7, 0xffff0000, v7
	v_pk_mul_f32 v[2:3], v[2:3], v[8:9]
	v_pk_mul_f32 v[4:5], v[4:5], v[6:7]
	v_cvt_pk_bf16_f32 v2, v2, v3
	v_cvt_pk_bf16_f32 v3, v4, v5
	global_store_dwordx2 v[10:11], v[2:3], off offset:2080
	s_barrier
	s_cbranch_scc1 .LBB0_816

	.amdhsa_kernel _Z4mega6Params
		.amdhsa_group_segment_fixed_size 148752
		.amdhsa_private_segment_fixed_size 0
		.amdhsa_kernarg_size 584
		.amdhsa_user_sgpr_count 2
		.amdhsa_user_sgpr_dispatch_ptr 0
		.amdhsa_user_sgpr_queue_ptr 0
		.amdhsa_user_sgpr_kernarg_segment_ptr 1
		.amdhsa_user_sgpr_dispatch_id 0
		.amdhsa_user_sgpr_kernarg_preload_length 0
		.amdhsa_user_sgpr_kernarg_preload_offset 0
		.amdhsa_user_sgpr_private_segment_size 0
		.amdhsa_uses_dynamic_stack 0
		.amdhsa_enable_private_segment 0
		.amdhsa_system_sgpr_workgroup_id_x 1
		.amdhsa_system_sgpr_workgroup_id_y 0
		.amdhsa_system_sgpr_workgroup_id_z 0
		.amdhsa_system_sgpr_workgroup_info 0
		.amdhsa_system_vgpr_workitem_id 2
		.amdhsa_next_free_vgpr 254
		.amdhsa_next_free_sgpr 100
		.amdhsa_accum_offset 256
		.amdhsa_reserve_vcc 1
		.amdhsa_float_round_mode_32 0
		.amdhsa_float_round_mode_16_64 0
		.amdhsa_float_denorm_mode_32 3
		.amdhsa_float_denorm_mode_16_64 3
		.amdhsa_dx10_clamp 1
		.amdhsa_ieee_mode 1
		.amdhsa_fp16_overflow 0
		.amdhsa_tg_split 0
		.amdhsa_exception_fp_ieee_invalid_op 0
		.amdhsa_exception_fp_denorm_src 0
		.amdhsa_exception_fp_ieee_div_zero 0
		.amdhsa_exception_fp_ieee_overflow 0
		.amdhsa_exception_fp_ieee_underflow 0
		.amdhsa_exception_fp_ieee_inexact 0
		.amdhsa_exception_int_div_zero 0
	.end_amdhsa_kernel

amdhsa.kernels:
  - .agpr_count:     0
    .args:
      - .offset:         0
        .size:           328
        .value_kind:     by_value
      - .offset:         328
        .size:           4
        .value_kind:     hidden_block_count_x
      - .offset:         332
        .size:           4
        .value_kind:     hidden_block_count_y
      - .offset:         336
        .size:           4
        .value_kind:     hidden_block_count_z
      - .offset:         340
        .size:           2
        .value_kind:     hidden_group_size_x
      - .offset:         342
        .size:           2
        .value_kind:     hidden_group_size_y
      - .offset:         344
        .size:           2
        .value_kind:     hidden_group_size_z
      - .offset:         346
        .size:           2
        .value_kind:     hidden_remainder_x
      - .offset:         348
        .size:           2
        .value_kind:     hidden_remainder_y
      - .offset:         350
        .size:           2
        .value_kind:     hidden_remainder_z
      - .offset:         368
        .size:           8
        .value_kind:     hidden_global_offset_x
      - .offset:         376
        .size:           8
        .value_kind:     hidden_global_offset_y
      - .offset:         384
        .size:           8
        .value_kind:     hidden_global_offset_z
      - .offset:         392
        .size:           2
        .value_kind:     hidden_grid_dims
      - .offset:         416
        .size:           8
        .value_kind:     hidden_multigrid_sync_arg
    .group_segment_fixed_size: 148752
    .kernarg_segment_align: 8
    .kernarg_segment_size: 584
    .language:       OpenCL C
    .language_version:
      - 2
      - 0
    .max_flat_workgroup_size: 512
    .name:           _Z4mega6Params
    .private_segment_fixed_size: 0
    .sgpr_count:     106
    .sgpr_spill_count: 124
    .symbol:         _Z4mega6Params.kd
    .uniform_work_group_size: 1
    .uses_dynamic_stack: false
    .vgpr_count:     254
    .vgpr_spill_count: 0
    .wavefront_size: 64
